# P5 prompt-chain loop: counted vmcnt, operands q/k/v/T/Aqk loaded cooperatively (dedup) and staged via LDS, no register-copy rotation
# speedup vs baseline: 1.0351x; 1.0198x over previous
.LBB0_2518:
	s_lshl_b32 s33, s4, 4
	v_and_or_b32 v117, s33, 48, v1
	v_add_u32_e32 v96, s6, v117
	v_mov_b32_e32 v97, 0
	s_and_b32 s38, s2, 7
	s_waitcnt lgkmcnt(0)
	v_lshlrev_b64 v[2:3], 11, v[96:97]
	s_mov_b32 s1, 0
	v_lshl_add_u64 v[4:5], s[64:65], 0, v[2:3]
	s_lshl_b32 s0, s38, 8
	v_mov_b32_e32 v36, v97
	v_mov_b32_e32 v37, v97
	v_lshl_add_u64 v[4:5], v[4:5], 0, s[0:1]
	v_lshlrev_b32_e32 v96, 1, v94
	v_mov_b32_e32 v34, v97
	v_mov_b32_e32 v35, v97
	v_mov_b64_e32 v[52:53], v[36:37]
	v_cmp_gt_u32_e32 vcc, s7, v117
	v_lshl_add_u64 v[4:5], v[4:5], 0, v[96:97]
	v_mov_b64_e32 v[50:51], v[34:35]
	s_and_saveexec_b64 s[0:1], vcc
	s_cbranch_execz .LBB0_2520
.LBB0_2520:
	s_or_b64 exec, exec, s[0:1]
	s_and_saveexec_b64 s[0:1], vcc
	s_cbranch_execz .LBB0_2522
.LBB0_2522:
	s_or_b64 exec, exec, s[0:1]
	v_mov_b32_e32 v6, 0
	v_mov_b32_e32 v8, v6
	v_mov_b32_e32 v9, v6
	v_mov_b32_e32 v7, v6
	v_mov_b64_e32 v[48:49], v[8:9]
	s_lshl_b32 s41, s38, 7
	v_mov_b64_e32 v[46:47], v[6:7]
	s_and_saveexec_b64 s[0:1], vcc
	s_cbranch_execz .LBB0_2524
.LBB0_2524:
	s_or_b64 exec, exec, s[0:1]
	s_mov_b32 s5, 0
	s_and_saveexec_b64 s[0:1], vcc
	s_cbranch_execz .LBB0_2526
.LBB0_2526:
	s_or_b64 exec, exec, s[0:1]
	s_and_b32 s8, s2, 0xffffffc0
	v_lshl_add_u64 v[2:3], s[14:15], 0, v[2:3]
	s_lshl_b32 s4, s41, 1
	s_lshr_b32 s0, s10, 3
	v_lshl_add_u64 v[2:3], v[2:3], 0, s[4:5]
	s_ashr_i32 s9, s8, 31
	s_and_b32 s16, s0, 0x1fffffe0
	v_lshl_add_u64 v[2:3], s[8:9], 1, v[2:3]
	s_lshl_b32 s10, s16, 1
	s_mov_b32 s11, s5
	v_mov_b32_e32 v95, 0
	v_lshl_add_u64 v[2:3], v[2:3], 0, s[10:11]
	v_mov_b32_e32 v108, v95
	v_mov_b32_e32 v109, v95
	v_lshl_add_u64 v[2:3], v[2:3], 0, v[94:95]
	v_mov_b64_e32 v[110:111], v[108:109]
	s_and_saveexec_b64 s[0:1], vcc
	s_cbranch_execz .LBB0_2528
.LBB0_2528:
	s_or_b64 exec, exec, s[0:1]
	s_and_saveexec_b64 s[0:1], vcc
	s_cbranch_execz .LBB0_2530
.LBB0_2530:
	s_or_b64 exec, exec, s[0:1]
	s_or_b32 s11, s44, s38
	s_lshl_b32 s0, s11, 14
	s_add_u32 s0, s62, s0
	s_addc_u32 s1, s63, 0
	v_lshlrev_b32_e32 v2, 7, v117
	v_mov_b32_e32 v3, 0
	v_lshl_add_u64 v[4:5], s[0:1], 0, v[2:3]
	v_mov_b32_e32 v97, v3
	v_lshl_add_u64 v[4:5], v[4:5], 0, v[96:97]
	s_mov_b64 s[0:1], 0x2000
	v_lshl_add_u64 v[10:11], v[4:5], 0, s[0:1]
	s_movk_i32 s0, 0x2000
	v_add_co_u32_e32 v14, vcc, s0, v4
	v_lshrrev_b32_e32 v118, 3, v116
	s_nop 0
	v_addc_co_u32_e32 v15, vcc, 0, v5, vcc
	v_mov_b32_e32 v4, v3
	v_mov_b32_e32 v5, v3
	v_and_b32_e32 v14, 7, v116
	v_mov_b32_e32 v2, v3
	v_mov_b64_e32 v[40:41], v[4:5]
	v_mov_b64_e32 v[44:45], v[4:5]
	v_lshlrev_b32_e32 v95, 2, v13
	v_cmp_gt_u32_e32 vcc, s7, v118
	v_lshlrev_b32_e32 v10, 5, v14
	v_mov_b64_e32 v[38:39], v[2:3]
	v_mov_b64_e32 v[42:43], v[2:3]
	s_and_saveexec_b64 s[0:1], vcc
	s_cbranch_execz .LBB0_2532
	v_add_u32_e32 v4, s6, v118
	v_mov_b32_e32 v5, 0
	v_lshlrev_b64 v[16:17], 11, v[4:5]
	v_lshl_add_u64 v[16:17], s[20:21], 0, v[16:17]
	v_lshl_add_u64 v[16:17], v[16:17], 0, s[4:5]
	v_mov_b32_e32 v11, v5
	v_lshl_add_u64 v[4:5], v[16:17], 0, v[10:11]

.LBB0_2534:
	s_or_b64 exec, exec, s[6:7]
	s_and_b32 s35, s2, 63
	s_add_u32 s6, s64, s4
	s_addc_u32 s7, s65, 0
	v_mov_b32_e32 v2, 0
	v_mov_b32_e32 v97, v2
	s_add_u32 s5, s14, s4
	v_lshl_add_u64 v[98:99], s[6:7], 0, v[96:97]
	s_addc_u32 s12, s15, 0
	s_lshl_b64 s[6:7], s[8:9], 1
	s_add_u32 s6, s5, s6
	s_addc_u32 s7, s12, s7
	s_add_u32 s12, s6, s10
	s_addc_u32 s13, s7, 0
	v_lshlrev_b32_e32 v5, 4, v14
	v_lshlrev_b32_e32 v14, 1, v95
	v_mov_b32_e32 v15, v2
	s_add_u32 s4, s20, s4
	v_lshl_add_u64 v[100:101], s[12:13], 0, v[14:15]
	s_addc_u32 s5, s21, 0
	s_add_i32 s18, 0, 0x11400
	s_lshl_b32 s12, s38, 5
	s_add_u32 s12, s28, s12
	s_addc_u32 s13, s29, 0
	v_mov_b32_e32 v11, v2
	s_add_u32 s12, s12, 0xf191400
	v_or_b32_e32 v16, s16, v1
	v_or_b32_e32 v17, s16, v95
	v_lshl_add_u64 v[102:103], s[4:5], 0, v[10:11]
	v_lshlrev_b32_e32 v10, 4, v13
	s_addc_u32 s13, s13, 0
	v_lshl_add_u64 v[104:105], s[6:7], 0, v[14:15]
	s_add_i32 s6, 0, 0x15c00
	s_movk_i32 s7, 0x90
	v_add_u32_e32 v18, s18, v10
	v_add_u32_e32 v14, s6, v10
	v_mul_lo_u32 v10, v17, s7
	v_lshlrev_b32_e32 v11, 1, v117
	v_mul_lo_u32 v125, v16, s7
	s_movk_i32 s7, 0x48
	v_add3_u32 v123, 0, v10, v11
	v_mul_lo_u32 v10, v17, s7
	v_add_lshl_u32 v10, v10, v117, 1
	v_add_u32_e32 v11, 0x90, v10
	v_add_u32_e32 v128, s18, v11
	v_add_u32_e32 v129, s6, v11
	v_add_u32_e32 v11, 0x120, v10
	v_add_u32_e32 v130, s18, v11
	v_add_u32_e32 v131, s6, v11
	v_add_u32_e32 v11, 0x1b0, v10
	v_add_u32_e32 v132, s18, v11
	v_add_u32_e32 v133, s6, v11
	v_add_u32_e32 v11, 0x900, v10
	v_add_u32_e32 v134, s18, v11
	v_add_u32_e32 v135, s6, v11
	v_add_u32_e32 v11, 0x990, v10
	v_add_u32_e32 v126, s18, v10
	v_add_u32_e32 v127, s6, v10
	v_add_u32_e32 v136, s18, v11
	v_add_u32_e32 v137, s6, v11
	v_add_u32_e32 v11, 0xa20, v10
	v_add_u32_e32 v10, 0xab0, v10
	v_add_u32_e32 v139, s6, v11
	v_add_u32_e32 v141, s6, v10
	s_add_i32 s6, s16, s8
	s_ashr_i32 s16, s6, 4
	s_add_i32 s6, s6, 16
	s_add_i32 s44, s44, s38
	v_add_u32_e32 v138, s18, v11
	v_add_u32_e32 v140, s18, v10
	s_ashr_i32 s18, s6, 4
	s_lshl_b32 s6, s44, 14
	s_mul_i32 s40, s40, 0x8400
	s_add_i32 s38, s6, 0x20000
	s_or_b32 s6, s41, s40
	v_add_lshl_u32 v10, s6, v116, 2
	v_mov_b32_e32 v11, v2
	s_movk_i32 s17, 0x110
	v_lshl_add_u64 v[10:11], s[28:29], 0, v[10:11]
	s_mov_b64 s[6:7], 0xf006400
	s_lshr_b32 s45, s44, 3
	v_or_b32_e32 v119, 32, v94
	s_mov_b32 s11, 0
	v_lshl_add_u32 v122, v94, 1, 0
	v_mul_lo_u32 v15, v16, s17
	v_mul_u32_u24_e32 v16, 0x90, v1
	v_lshl_add_u64 v[106:107], v[10:11], 0, s[6:7]
	s_lshl_b32 s6, s45, 6
	v_add_u32_e32 v148, v12, v4
	v_mbcnt_lo_u32_b32 v4, -1, 0
	v_mul_u32_u24_e32 v120, 0x110, v118
	v_mul_u32_u24_e32 v121, 0x110, v117
	v_cmp_eq_u32_e64 s[4:5], 0, v13
	v_add_u32_e32 v124, 0x900, v123
	s_ashr_i32 s17, s16, 31
	s_ashr_i32 s19, s18, 31
	v_mul_u32_u24_e32 v142, 0x880, v13
	v_mul_u32_u24_e32 v143, 0x110, v119
	s_mov_b32 s39, s11
	s_sub_i32 s46, s6, 64
	s_sub_i32 s47, 0, s45
	v_lshlrev_b32_e32 v144, 1, v5
	v_add_u32_e32 v145, v122, v15
	v_add_u32_e32 v146, v18, v125
	s_mov_b32 s48, 0x5040100
	v_add_u32_e32 v147, v14, v16
	s_mov_b64 s[40:41], 0x1000
	v_mbcnt_hi_u32_b32 v149, -1, v4
	s_mov_b32 s49, s44
	s_mov_b32 s50, s11
	s_mov_b32 s51, s11
	v_mov_b32_e32 v22, 0
	v_mov_b32_e32 v23, v2
	v_mov_b32_e32 v24, v2
	v_mov_b32_e32 v25, v2
	v_mov_b32_e32 v18, 0
	v_mov_b32_e32 v19, v2
	v_mov_b32_e32 v20, v2
	v_mov_b32_e32 v21, v2
	v_mov_b32_e32 v14, 0
	v_mov_b32_e32 v15, v2
	v_mov_b32_e32 v16, v2
	v_mov_b32_e32 v17, v2
	v_mov_b32_e32 v10, 0
	v_mov_b32_e32 v11, v2
	v_mov_b32_e32 v12, v2
	v_mov_b32_e32 v13, v2
	v_and_b32_e32 v222, 7, v116
	v_lshlrev_b32_e32 v223, 4, v222
	v_lshlrev_b32_e32 v225, 5, v222
	v_add_u32_e32 v204, v120, v225
	v_add_u32_e32 v205, v121, v96
	v_mul_u32_u24_e32 v216, 0x90, v118
	v_add_u32_e32 v216, v216, v223
	v_add_u32_e32 v217, 0x13800, v216
	v_add_u32_e32 v218, 0x18000, v216
	v_mul_u32_u24_e32 v219, 0x90, v117
	v_add_u32_e32 v221, v219, v94
	v_add_u32_e32 v221, s10, v221
	v_add_u32_e32 v221, 0x18000, v221
	v_add_u32_e32 v219, v219, v96
	v_add_u32_e32 v220, 0x13800, v219
	s_and_b32 s66, s2, 7
	s_bfe_u32 s67, s2, 0x30003
	s_lshl_b32 s68, s66, 8
	s_and_b32 s69, s2, 64
	s_lshl_b32 s69, s69, 1
	v_lshlrev_b32_e32 v224, 11, v118
	v_add_u32_e32 v224, s68, v224
	v_mov_b32_e32 v227, 0
	v_mov_b32_e32 v229, 0
	v_add_u32_e32 v226, v224, v225
	v_add_u32_e32 v228, v224, v223
	v_add_u32_e32 v228, s69, v228
	s_lshl_b32 s70, s67, 4
	s_add_i32 s70, s70, 0x4400
	s_lshl_b32 s70, s70, 11
	s_add_u32 s36, s20, s70
	s_addc_u32 s37, s21, 0
	v_lshl_add_u64 v[206:207], s[36:37], 0, v[226:227]
	s_add_u32 s36, s64, s70
	s_addc_u32 s37, s65, 0
	v_lshl_add_u64 v[208:209], s[36:37], 0, v[226:227]
	s_add_u32 s36, s14, s70
	s_addc_u32 s37, s15, 0
	v_lshl_add_u64 v[210:211], s[36:37], 0, v[228:229]
	s_mul_i32 s70, s67, 0x108
	s_add_i32 s70, s70, s66
	s_lshl_b32 s71, s70, 14
	s_add_u32 s36, s62, s71
	s_addc_u32 s37, s63, 0
	v_lshlrev_b32_e32 v230, 4, v116
	v_mov_b32_e32 v231, 0
	v_lshl_add_u64 v[212:213], s[36:37], 0, v[230:231]
	v_add_u32_e32 v230, 0x2000, v230
	v_lshl_add_u64 v[214:215], s[36:37], 0, v[230:231]
	v_mov_b32_e32 v38, 0
	v_mov_b32_e32 v39, 0
	v_mov_b64_e32 v[40:41], v[38:39]
	v_mov_b64_e32 v[42:43], v[38:39]
	v_mov_b64_e32 v[44:45], v[38:39]
	v_mov_b64_e32 v[62:63], v[38:39]
	v_mov_b64_e32 v[64:65], v[38:39]
	v_mov_b64_e32 v[66:67], v[38:39]
	v_mov_b64_e32 v[68:69], v[38:39]
	v_mov_b64_e32 v[78:79], v[38:39]
	v_mov_b64_e32 v[80:81], v[38:39]
	v_cmp_gt_u32_e32 vcc, 16, v118
	s_and_saveexec_b64 s[70:71], vcc
	global_load_dwordx4 v[42:45], v[206:207], off
	global_load_dwordx4 v[38:41], v[206:207], off offset:16
	global_load_dwordx4 v[62:65], v[208:209], off
	global_load_dwordx4 v[66:69], v[208:209], off offset:16
	global_load_dwordx4 v[78:81], v[210:211], off
	s_or_b64 exec, exec, s[70:71]
	global_load_dwordx4 v[70:73], v[212:213], off
	global_load_dwordx4 v[74:77], v[214:215], off
	s_lshl_b32 s70, s67, 22
	s_add_u32 s36, s20, s70
	s_addc_u32 s37, s21, 0
	v_lshl_add_u64 v[206:207], s[36:37], 0, v[226:227]
	s_add_u32 s36, s64, s70
	s_addc_u32 s37, s65, 0
	v_lshl_add_u64 v[208:209], s[36:37], 0, v[226:227]
	s_add_u32 s36, s14, s70
	s_addc_u32 s37, s15, 0
	v_lshl_add_u64 v[210:211], s[36:37], 0, v[228:229]
	s_mov_b32 s36, 0x20000
	s_mov_b32 s37, 0
	v_lshl_add_u64 v[212:213], v[212:213], 0, s[36:37]
	v_lshl_add_u64 v[214:215], v[214:215], 0, s[36:37]
	s_waitcnt vmcnt(0)
	s_branch .LBB0_2537

.LBB0_2536:
	s_or_b64 exec, exec, s[6:7]
	s_add_i32 s52, s52, s3
	v_lshl_add_u32 v51, v1, 1, s52
	v_add_u32_e32 v52, v51, v142
	v_mul_f32_e32 v4, 0x3fb8aa3b, v50
	ds_read_u16 v8, v52 offset:34816
	ds_read_u16 v9, v52 offset:35088
	ds_read_u16 v26, v52 offset:35360
	s_waitcnt lgkmcnt(3)
	ds_read_u16 v27, v52 offset:35632
	ds_read_u16 v28, v52 offset:35904
	ds_read_u16 v29, v52 offset:36448
	ds_read_u16 v30, v52 offset:36720
	ds_read_u16 v31, v52 offset:36176
	v_exp_f32_e32 v50, v4
	s_add_i32 s50, s50, 8
	s_add_u32 s38, s38, 0x20000
	s_addc_u32 s39, s39, 0
	v_pk_mul_f32 v[6:7], v[24:25], v[50:51] op_sel_hi:[1,0]
	v_pk_mul_f32 v[4:5], v[22:23], v[50:51] op_sel_hi:[1,0]
	s_waitcnt lgkmcnt(1)
	v_perm_b32 v25, v30, v29, s48
	s_waitcnt lgkmcnt(0)
	v_perm_b32 v24, v31, v28, s48
	v_perm_b32 v23, v27, v26, s48
	v_perm_b32 v22, v9, v8, s48
	ds_read_b128 v[26:29], v147
	v_pk_mul_f32 v[8:9], v[16:17], v[50:51] op_sel_hi:[1,0]
	ds_read_b128 v[30:33], v147 offset:2304
	ds_read_b128 v[34:37], v147 offset:64
	s_waitcnt lgkmcnt(2)
	v_mfma_f32_16x16x32_bf16 v[26:29], v[22:25], v[26:29], v[4:7]
	v_mul_f32_e64 v20, v20, v50
	v_mul_f32_e64 v21, v21, v50
	s_nop 0
	v_pk_mul_f32 v[6:7], v[14:15], v[50:51] op_sel_hi:[1,0]
	ds_read_b128 v[14:17], v147 offset:4608
	ds_read_b128 v[46:49], v147 offset:2368
	v_pk_mul_f32 v[18:19], v[18:19], v[50:51] op_sel_hi:[1,0]
	s_waitcnt lgkmcnt(1)
	v_mfma_f32_16x16x32_bf16 v[4:7], v[22:25], v[14:17], v[6:9]
	v_mul_f32_e64 v12, v12, v50
	v_mul_f32_e64 v13, v13, v50
	s_nop 0
	v_add_u32_e32 v8, v51, v143
	v_pk_mul_f32 v[10:11], v[10:11], v[50:51] op_sel_hi:[1,0]
	v_mfma_f32_16x16x32_bf16 v[18:21], v[22:25], v[30:33], v[18:21]
	ds_read_b128 v[30:33], v147 offset:4672
	ds_read_b128 v[14:17], v147 offset:6912
	ds_read_u16 v54, v52 offset:43792
	ds_read_u16 v55, v52 offset:44064
	ds_read_u16 v58, v52 offset:44336
	ds_read_u16 v56, v52 offset:44608
	ds_read_u16 v59, v52 offset:44880
	ds_read_u16 v57, v52 offset:45152
	ds_read_u16 v60, v52 offset:45424
	ds_read_u16 v61, v8 offset:34816
	ds_read_b128 v[50:53], v147 offset:6976
	s_waitcnt lgkmcnt(6)
	v_perm_b32 v55, v58, v55, s48
	s_waitcnt lgkmcnt(4)
	v_perm_b32 v56, v59, v56, s48
	v_mfma_f32_16x16x32_bf16 v[8:11], v[22:25], v[14:17], v[10:13]
	s_waitcnt lgkmcnt(2)
	v_perm_b32 v57, v60, v57, s48
	s_waitcnt lgkmcnt(1)
	v_perm_b32 v54, v54, v61, s48
	s_add_i32 s46, s46, 64
	s_add_i32 s49, s49, 8
	v_mfma_f32_16x16x32_bf16 v[22:25], v[54:57], v[34:37], v[26:29]
	s_add_i32 s45, s45, 1
	s_add_i32 s51, s51, 1
	v_mfma_f32_16x16x32_bf16 v[18:21], v[54:57], v[46:49], v[18:21]
	v_mfma_f32_16x16x32_bf16 v[14:17], v[54:57], v[30:33], v[4:7]
	v_lshl_add_u64 v[106:107], v[106:107], 0, s[40:41]
	s_cmpk_lg_i32 s50, 0x108
	s_waitcnt lgkmcnt(0)
	v_mfma_f32_16x16x32_bf16 v[10:13], v[54:57], v[50:53], v[8:11]
	v_cvt_pk_bf16_f32 v4, v22, v23
	v_cvt_pk_bf16_f32 v5, v24, v25
	ds_write_b64 v148, v[4:5]
	v_cvt_pk_bf16_f32 v4, v18, v19
	v_cvt_pk_bf16_f32 v5, v20, v21
	ds_write_b64 v148, v[4:5] offset:4352
	v_cvt_pk_bf16_f32 v4, v14, v15
	v_cvt_pk_bf16_f32 v5, v16, v17
	ds_write_b64 v148, v[4:5] offset:8704
	v_cvt_pk_bf16_f32 v4, v10, v11
	v_cvt_pk_bf16_f32 v5, v12, v13
	ds_write_b64 v148, v[4:5] offset:13056
	s_cbranch_scc0 .LBB0_2580

.LBB0_2540:
	s_and_b32 s6, s51, 1
	s_mul_i32 s7, s6, 0x12000
	s_mulk_i32 s6, 0x4800
	s_add_i32 s55, s6, 0
	s_add_i32 s52, s7, 0
	s_add_i32 s55, s55, 0x1a400
	v_add3_u32 v4, s52, v120, v144
	s_waitcnt vmcnt(4)
	ds_write_b128 v4, v[42:45] offset:34816
	ds_write_b128 v4, v[38:41] offset:34832
	ds_write_b128 v204, v[62:65] offset:17408
	ds_write_b128 v204, v[66:69] offset:17424
	ds_write_b128 v216, v[70:73] offset:61440
	ds_write_b128 v217, v[74:77]
	ds_write_b128 v218, v[78:81]
	s_and_saveexec_b64 s[6:7], s[0:1]
	v_lshl_add_u32 v4, v116, 2, s55
	ds_write_b32 v4, v3
	s_or_b64 exec, exec, s[6:7]
	s_cmpk_eq_i32 s50, 0x100
	s_waitcnt lgkmcnt(0)
	s_barrier
	s_cbranch_scc1 .LBB0_2572
	global_load_dwordx4 v[42:45], v[206:207], off
	global_load_dwordx4 v[38:41], v[206:207], off offset:16
	global_load_dwordx4 v[62:65], v[208:209], off
	global_load_dwordx4 v[66:69], v[208:209], off offset:16
	global_load_dwordx4 v[78:81], v[210:211], off
	global_load_dwordx4 v[70:73], v[212:213], off
	global_load_dwordx4 v[74:77], v[214:215], off
	s_and_saveexec_b64 s[6:7], s[0:1]
	global_load_dword v3, v[106:107], off
	s_or_b64 exec, exec, s[6:7]
	v_lshl_add_u64 v[206:207], v[206:207], 0, s[36:37]
	v_lshl_add_u64 v[208:209], v[208:209], 0, s[36:37]
	v_lshl_add_u64 v[210:211], v[210:211], 0, s[36:37]
	v_lshl_add_u64 v[212:213], v[212:213], 0, s[36:37]
	v_lshl_add_u64 v[214:215], v[214:215], 0, s[36:37]
.LBB0_2572:
	ds_read_b128 v[50:53], v205 offset:17408
	ds_read_b128 v[34:37], v205 offset:17472
	ds_read_b128 v[46:49], v205 offset:17536
	ds_read_b128 v[6:9], v205 offset:17600
	ds_read_b64 v[110:111], v221
	ds_read_b64 v[108:109], v221 offset:32
	ds_read_b128 v[150:153], v145
	v_add3_u32 v97, s52, v121, v96
	ds_read_b128 v[154:157], v97 offset:34816
	ds_read_b128 v[158:161], v97 offset:35008
	ds_read_b128 v[166:169], v145 offset:4352
	v_lshl_add_u32 v4, v117, 2, s55
	ds_read_b128 v[170:173], v145 offset:64
	ds_read_b128 v[174:177], v145 offset:192
	ds_read2st64_b32 v[4:5], v4 offset1:1
	ds_read_b128 v[178:181], v97 offset:34880
	ds_read_b128 v[182:185], v145 offset:128
	s_waitcnt lgkmcnt(7)
	v_mfma_f32_16x16x32_bf16 v[162:165], v[150:153], v[154:157], 0
	v_mfma_f32_16x16x32_bf16 v[150:153], v[150:153], v[50:53], 0
	s_waitcnt lgkmcnt(5)
	v_mfma_f32_16x16x32_bf16 v[154:157], v[166:169], v[154:157], 0
	v_mfma_f32_16x16x32_bf16 v[166:169], v[166:169], v[50:53], 0
	v_mov_b32_e32 v50, s55
	ds_read_b32 v50, v50 offset:252
	ds_read_b128 v[186:189], v97 offset:34944
	ds_read_b128 v[190:193], v145 offset:4416
	ds_read_b128 v[194:197], v145 offset:4480
	s_waitcnt lgkmcnt(5)
	v_mfma_f32_16x16x32_bf16 v[162:165], v[170:173], v[178:181], v[162:165]
	ds_read_b128 v[198:201], v145 offset:4544
	v_mul_f32_e32 v51, 0x3fb8aa3b, v4
	v_exp_f32_e32 v202, v51
	s_waitcnt lgkmcnt(3)
	v_mfma_f32_16x16x32_bf16 v[162:165], v[182:185], v[186:189], v[162:165]
	v_lshlrev_b32_e32 v51, 16, v110
	v_and_b32_e32 v52, 0xffff0000, v110
	v_lshlrev_b32_e32 v53, 16, v111
	s_waitcnt lgkmcnt(2)
	v_mfma_f32_16x16x32_bf16 v[154:157], v[190:193], v[178:181], v[154:157]
	v_and_b32_e32 v97, 0xffff0000, v111
	v_sub_f32_e32 v4, v50, v4
	v_mul_f32_e32 v4, 0x3fb8aa3b, v4
	v_mfma_f32_16x16x32_bf16 v[162:165], v[174:177], v[158:161], v[162:165]
	v_exp_f32_e32 v4, v4
	s_waitcnt lgkmcnt(1)
	v_mfma_f32_16x16x32_bf16 v[154:157], v[194:197], v[186:189], v[154:157]
	v_mfma_f32_16x16x32_bf16 v[150:153], v[170:173], v[34:37], v[150:153]
	s_nop 3
	v_fma_f32 v51, -v202, v162, v51
	v_mul_f32_e32 v51, v5, v51
	v_fma_f32 v52, -v202, v163, v52
	v_mul_f32_e32 v52, v5, v52
	v_fma_f32 v53, -v202, v164, v53
	v_cvt_pk_bf16_f32 v51, v51, s0
	v_mul_f32_e32 v53, v5, v53
	v_mfma_f32_16x16x32_bf16 v[34:37], v[190:193], v[34:37], v[166:169]
	v_fma_f32 v97, -v202, v165, v97
	ds_write_b16 v123, v51 offset:52224
	v_cvt_pk_bf16_f32 v51, v52, s0
	s_waitcnt lgkmcnt(1)
	v_mfma_f32_16x16x32_bf16 v[154:157], v[198:201], v[158:161], v[154:157]
	v_mul_f32_e32 v97, v5, v97
	ds_write_b16 v123, v51 offset:52368
	v_cvt_pk_bf16_f32 v51, v53, s0
	ds_write_b16 v123, v51 offset:52512
	v_cvt_pk_bf16_f32 v51, v97, s0
	ds_write_b16 v123, v51 offset:52656
	v_lshlrev_b32_e32 v51, 16, v108
	v_mfma_f32_16x16x32_bf16 v[150:153], v[182:185], v[46:49], v[150:153]
	v_fma_f32 v51, -v202, v154, v51
	v_mul_f32_e32 v51, v5, v51
	v_lshlrev_b32_e32 v53, 16, v109
	v_mfma_f32_16x16x32_bf16 v[34:37], v[194:197], v[46:49], v[34:37]
	v_and_b32_e32 v46, 0xffff0000, v108
	v_fma_f32 v52, -v202, v155, v46
	v_and_b32_e32 v97, 0xffff0000, v109
	v_mul_f32_e32 v52, v5, v52
	v_fma_f32 v53, -v202, v156, v53
	v_fma_f32 v97, -v202, v157, v97
	v_cvt_pk_bf16_f32 v51, v51, s0
	v_mul_f32_e32 v53, v5, v53
	v_mul_f32_e32 v5, v5, v97
	ds_write_b16 v124, v51 offset:52224
	v_cvt_pk_bf16_f32 v51, v52, s0
	ds_write_b16 v124, v51 offset:52368
	v_cvt_pk_bf16_f32 v51, v53, s0
	v_cvt_pk_bf16_f32 v5, v5, s0
	ds_write_b16 v124, v51 offset:52512
	ds_write_b16 v124, v5 offset:52656
	s_waitcnt lgkmcnt(0)
	s_barrier
	v_add_u32_e32 v5, v122, v125
	v_mfma_f32_16x16x32_bf16 v[46:49], v[174:177], v[6:9], v[150:153]
	ds_read_b128 v[54:57], v219 offset:61440
	ds_read_b128 v[58:61], v219 offset:61504
	ds_read_b128 v[26:29], v220
	ds_read_b128 v[30:33], v220 offset:64
	ds_read_b128 v[108:111], v5 offset:52224
	s_nop 1
	ds_read_b128 v[150:153], v5 offset:52288
	ds_read_b128 v[154:157], v5 offset:54528
	ds_read_b128 v[158:161], v5 offset:54592
	s_waitcnt lgkmcnt(3)
	v_mfma_f32_16x16x32_bf16 v[108:111], v[108:111], v[54:57], 0
	s_waitcnt lgkmcnt(2)
	v_mfma_f32_16x16x32_bf16 v[108:111], v[150:153], v[58:61], v[108:111]
	s_waitcnt lgkmcnt(1)
	v_mfma_f32_16x16x32_bf16 v[52:55], v[154:157], v[54:57], 0
	s_waitcnt lgkmcnt(0)
	v_mfma_f32_16x16x32_bf16 v[52:55], v[158:161], v[58:61], v[52:55]
	s_nop 3
	v_cvt_pk_bf16_f32 v5, v108, s0
	ds_write_b16 v126, v5
	v_mul_f32_e32 v5, v4, v108
	v_cvt_pk_bf16_f32 v5, v5, s0
	ds_write_b16 v127, v5
	v_cvt_pk_bf16_f32 v5, v109, s0
	ds_write_b16 v128, v5
	v_mul_f32_e32 v5, v4, v109
	v_cvt_pk_bf16_f32 v5, v5, s0
	ds_write_b16 v129, v5
	v_cvt_pk_bf16_f32 v5, v110, s0
	ds_write_b16 v130, v5
	v_mul_f32_e32 v5, v4, v110
	v_cvt_pk_bf16_f32 v5, v5, s0
	ds_write_b16 v131, v5
	v_cvt_pk_bf16_f32 v5, v111, s0
	ds_write_b16 v132, v5
	v_mul_f32_e32 v5, v4, v111
	v_cvt_pk_bf16_f32 v5, v5, s0
	ds_write_b16 v133, v5
	v_cvt_pk_bf16_f32 v5, v52, s0
	ds_write_b16 v134, v5
	v_mul_f32_e32 v5, v4, v52
	v_cvt_pk_bf16_f32 v5, v5, s0
	ds_write_b16 v135, v5
	v_cvt_pk_bf16_f32 v5, v53, s0
	ds_write_b16 v136, v5
	v_mul_f32_e32 v5, v4, v53
	v_cvt_pk_bf16_f32 v5, v5, s0
	ds_write_b16 v137, v5
	v_cvt_pk_bf16_f32 v5, v54, s0
	ds_write_b16 v138, v5
	v_mul_f32_e32 v5, v4, v54
	v_cvt_pk_bf16_f32 v5, v5, s0
	v_mul_f32_e32 v4, v4, v55
	ds_write_b16 v139, v5
	v_cvt_pk_bf16_f32 v5, v55, s0
	v_cvt_pk_bf16_f32 v4, v4, s0
	ds_write_b16 v140, v5
	ds_write_b16 v141, v4
	s_waitcnt lgkmcnt(0)
	s_barrier
	ds_read_b128 v[52:55], v146
	ds_read_b128 v[56:59], v146 offset:2304
	v_mfma_f32_16x16x32_bf16 v[4:7], v[198:201], v[6:9], v[34:37]
	v_and_b32_e32 v9, 64, v149
	v_xor_b32_e32 v8, 16, v149
	v_add_u32_e32 v9, 64, v9
	v_pk_mul_f32 v[34:35], v[202:203], v[46:47] op_sel_hi:[0,1]
	v_pk_mul_f32 v[36:37], v[202:203], v[48:49] op_sel_hi:[0,1]
	ds_read_b128 v[46:49], v146 offset:64
	s_nop 1
	v_pk_mul_f32 v[4:5], v[202:203], v[4:5] op_sel_hi:[0,1]
	s_waitcnt lgkmcnt(2)
	v_mfma_f32_16x16x32_bf16 v[34:37], v[52:55], v[26:29], v[34:37]
	ds_read_b128 v[52:55], v146 offset:2368
	v_pk_mul_f32 v[6:7], v[202:203], v[6:7] op_sel_hi:[0,1]
	v_cmp_lt_i32_e32 vcc, v8, v9
	s_waitcnt lgkmcnt(2)
	v_mfma_f32_16x16x32_bf16 v[4:7], v[56:59], v[26:29], v[4:7]
	v_cndmask_b32_e32 v8, v149, v8, vcc
	s_waitcnt lgkmcnt(1)
	v_mfma_f32_16x16x32_bf16 v[26:29], v[46:49], v[30:33], v[34:37]
	s_waitcnt lgkmcnt(0)
	v_mfma_f32_16x16x32_bf16 v[4:7], v[52:55], v[30:33], v[4:7]
	v_lshlrev_b32_e32 v32, 2, v8
	v_xor_b32_e32 v8, 32, v149
	v_cmp_lt_i32_e32 vcc, v8, v9
	s_nop 2
	v_mul_f32_e32 v9, v27, v27
	v_mul_f32_e32 v30, v29, v29
	v_fmac_f32_e32 v9, v26, v26
	v_fmac_f32_e32 v30, v28, v28
	v_add_f32_e32 v30, v9, v30
	ds_bpermute_b32 v31, v32, v30
	v_cndmask_b32_e32 v8, v149, v8, vcc
	v_lshlrev_b32_e32 v33, 2, v8
	v_add_u32_e32 v8, s53, v117
	v_mov_b32_e32 v9, v2
	s_waitcnt lgkmcnt(0)
	v_add_f32_e32 v34, v30, v31
	ds_bpermute_b32 v35, v33, v34
	v_lshlrev_b64 v[30:31], 8, v[8:9]
	v_lshlrev_b64 v[8:9], 11, v[8:9]
	v_cmp_gt_u32_e32 vcc, s54, v117
	v_lshl_add_u64 v[30:31], s[12:13], 0, v[30:31]
	v_lshl_add_u64 v[8:9], v[104:105], 0, v[8:9]
	s_and_saveexec_b64 s[6:7], vcc
	s_and_saveexec_b64 s[42:43], s[4:5]
	s_waitcnt lgkmcnt(0)
	v_add_f32_e32 v36, v34, v35
	v_lshl_add_u64 v[34:35], s[16:17], 2, v[30:31]
	global_store_dword v[34:35], v36, off

.LBB0_2576:
	s_or_b64 exec, exec, s[6:7]
	v_mul_f32_e32 v26, v5, v5
	v_mul_f32_e32 v27, v7, v7
	v_fmac_f32_e32 v26, v4, v4
	v_fmac_f32_e32 v27, v6, v6
	v_add_f32_e32 v26, v26, v27
	ds_bpermute_b32 v27, v32, v26
	s_waitcnt lgkmcnt(0)
	v_add_f32_e32 v26, v26, v27
	ds_bpermute_b32 v27, v33, v26
	s_and_saveexec_b64 s[6:7], vcc
	s_and_saveexec_b64 s[42:43], s[4:5]
	s_waitcnt lgkmcnt(0)
	v_add_f32_e32 v28, v26, v27
	v_lshl_add_u64 v[26:27], s[18:19], 2, v[30:31]
	global_store_dword v[26:27], v28, off
	s_branch .LBB0_2535
